# MLA phase: equal wave priority (the static raise of waves 4-7 dropped)
# baseline (speedup 1.0000x reference)
.LBB0_2691:
	s_or_b64 exec, exec, s[10:11]
	s_cmpk_gt_i32 s3, 0x83f
	s_waitcnt lgkmcnt(0)
	s_barrier
	s_cbranch_scc1 .LBB0_2732
	v_readfirstlane_b32 s4, v146
	s_nop 1
	s_cmpk_lt_u32 s4, 0x100
	s_cbranch_scc1 .Lmla_prio_done
.Lmla_prio_done:
	v_and_b32_e32 v4, 31, v146
	v_lshrrev_b32_e32 v0, 1, v146
	s_movk_i32 s2, 0x1e0
	v_and_or_b32 v153, v0, s2, v4
	v_add_u32_e32 v5, 0x200, v146
	s_movk_i32 s2, 0x100
	v_cmp_gt_u32_e64 s[10:11], s2, v146
	v_mul_u32_u24_e32 v7, 0x1556, v146
	v_mul_u32_u24_e32 v9, 0x1556, v5
	s_mov_b32 s2, 0x7060302
	v_lshrrev_b32_e32 v8, 16, v7
	v_lshrrev_b32_e32 v10, 16, v9
	v_perm_b32 v7, v9, v7, s2
	s_movk_i32 s4, 0x68
	v_mad_i32_i24 v5, v10, -12, v5
	v_pk_mul_lo_u16 v7, v7, s4 op_sel_hi:[1,0]
	v_bfe_u32 v1, v146, 5, 1
	v_and_b32_e32 v6, 56, v147
	v_lshlrev_b32_e32 v142, 3, v5
	v_lshrrev_b32_e32 v180, 16, v7
	v_lshlrev_b32_e32 v5, 4, v5
	v_lshlrev_b32_e32 v0, 3, v1
	v_lshl_add_u32 v181, v180, 1, v5
	v_lshlrev_b32_e32 v158, 1, v6
	v_mul_u32_u24_e32 v5, 0x68, v4
	v_lshlrev_b32_e32 v6, 4, v1
	v_lshlrev_b32_e32 v253, 2, v1
	v_mbcnt_hi_u32_b32 v1, -1, v145
	v_lshl_add_u32 v184, v5, 1, v6
	v_and_b32_e32 v5, 64, v1
	v_mov_b32_e32 v97, 0
	v_mul_u32_u24_e32 v96, 0x4200, v154
	v_mad_i32_i24 v9, v8, -12, v146
	v_mul_u32_u24_e32 v185, 0x48, v4
	v_xor_b32_e32 v4, 32, v1
	v_add_u32_e32 v5, 64, v5
	v_lshl_add_u64 v[2:3], s[12:13], 0, v[96:97]
	v_lshlrev_b32_e32 v138, 3, v9
	v_ashrrev_i32_e32 v143, 31, v142
	v_cmp_lt_i32_e32 vcc, v4, v5
	v_mov_b32_e32 v159, v97
	s_movk_i32 s2, 0xc00
	v_ashrrev_i32_e32 v139, 31, v138
	v_cndmask_b32_e32 v1, v1, v4, vcc
	v_lshl_add_u64 v[162:163], v[2:3], 0, v[158:159]
	v_lshlrev_b64 v[2:3], 1, v[142:143]
	v_and_b32_e32 v11, 0xfff8, v7
	v_lshlrev_b32_e32 v9, 4, v9
	v_mul_u32_u24_e32 v182, 0x48, v154
	v_lshlrev_b32_e32 v186, 2, v1
	v_and_b32_e32 v1, 7, v146
	v_mad_u64_u32 v[166:167], s[4:5], v10, s2, v[2:3]
	v_lshlrev_b64 v[2:3], 1, v[138:139]
	v_mul_hi_u32_u24_e32 v137, 0xc00, v8
	v_mul_u32_u24_e32 v136, 0xc00, v8
	v_mul_u32_u24_e32 v140, 0xc00, v10
	v_mov_b32_e32 v141, v97
	v_lshl_add_u32 v161, v11, 1, v9
	v_lshl_add_u32 v183, v182, 1, v158
	s_mov_b32 s39, 0
	v_lshl_or_b32 v159, v185, 1, v0
	v_lshl_or_b32 v164, v1, 4, v96
	v_mov_b32_e32 v165, v97
	v_mad_u64_u32 v[168:169], s[4:5], v8, s2, v[2:3]
	v_mov_b32_e32 v187, 0x2100
	v_mov_b64_e32 v[170:171], s[94:95]
	v_lshlrev_b32_e32 v172, 1, v0
	v_mov_b32_e32 v173, v97
	v_mov_b32_e32 v188, 0x108000
	v_mov_b32_e32 v189, 0xc0
	s_mov_b64 s[40:41], 0x100
	s_mov_b64 s[42:43], 0x60000
	v_lshlrev_b32_e32 v190, 1, v11
	s_mov_b32 s6, s3
	v_mov_b32_e32 v252, 0x12000
	v_lshl_add_u32 v252, v146, 6, v252
	v_add_u32_e32 v177, v180, v142
	v_lshlrev_b32_e32 v177, 1, v177
	v_lshl_add_u32 v179, v138, 1, v190
	s_branch .LBB0_2694
